# static s_setprio 1 for waves 4-7 during the attention item compute block
# baseline (speedup 1.0000x reference)
.LBB0_361:
	v_lshrrev_b32_e32 v15, 6, v0
	v_and_b32_e32 v16, 15, v0
	v_bfe_u32 v148, v0, 4, 2
	v_readfirstlane_b32 s92, v15
	v_lshl_or_b32 v17, v15, 5, v16
	v_lshlrev_b32_e32 v146, 2, v148
	v_sub_u32_e32 v14, v16, v146
	v_mov_b32_e32 v15, 0x90
	v_mul_u32_u24_e32 v194, v17, v15
	v_lshl_add_u32 v194, v148, 4, v194
	v_add_u32_e32 v194, 16, v194
	v_lshrrev_b32_e32 v195, 2, v16
	v_add_u32_e32 v195, v195, v146
	v_lshl_add_u32 v195, s92, 5, v195
	v_mul_u32_u24_e32 v195, v195, v15
	v_and_b32_e32 v16, 3, v0
	v_lshl_add_u32 v195, v16, 3, v195
	v_add_u32_e32 v195, 0xd810, v195
	ds_read_b128 v[178:181], v194 offset:0
	ds_read_b128 v[182:185], v194 offset:64
	ds_read_b128 v[186:189], v194 offset:2304
	ds_read_b128 v[190:193], v194 offset:2368
	ds_read_b64_tr_b16 v[200:201], v195 offset:0
	ds_read_b64_tr_b16 v[202:203], v195 offset:2304
	ds_read_b64_tr_b16 v[204:205], v195 offset:32
	ds_read_b64_tr_b16 v[206:207], v195 offset:2336
	ds_read_b64_tr_b16 v[208:209], v195 offset:64
	ds_read_b64_tr_b16 v[210:211], v195 offset:2368
	ds_read_b64_tr_b16 v[212:213], v195 offset:96
	ds_read_b64_tr_b16 v[214:215], v195 offset:2400
	v_lshrrev_b32_e32 v15, 3, v0
	v_and_b32_e32 v16, 7, v0
	v_lshlrev_b32_e32 v16, 4, v16
	v_mad_u32_u24 v196, v15, s95, v16
	v_and_b32_e32 v16, 48, v0
	v_mad_u32_u24 v198, v17, s95, v16
	s_lshl_b32 s60, s95, 6
	s_lshl_b32 s61, s95, 4
	s_sub_i32 s93, 4, s92
	s_max_i32 s93, s93, 0
	s_cmp_eq_u32 s17, 0
	s_cselect_b32 s93, 0, s93
	v_cmp_le_i32_e64 s[76:77], v14, 0
	v_cmp_le_i32_e64 s[78:79], v14, 1
	v_cmp_le_i32_e64 s[80:81], v14, 2
	v_cmp_le_i32_e64 s[82:83], v14, 3
	v_cmp_ge_i32_e64 s[84:85], v14, 0
	v_cmp_ge_i32_e64 s[86:87], v14, 1
	v_cmp_ge_i32_e64 s[88:89], v14, 2
	v_cmp_ge_i32_e64 s[90:91], v14, 3
	v_mov_b32_e32 v10, 0x3f803f80
	v_mov_b32_e32 v11, v10
	v_mov_b32_e32 v12, v10
	v_mov_b32_e32 v13, v10
	v_mov_b32_e32 v138, 0
	v_mov_b32_e32 v139, 0
	v_mov_b32_e32 v140, 0
	v_mov_b32_e32 v141, 0
	v_mov_b32_e32 v118, 0
	v_mov_b32_e32 v119, 0
	v_mov_b32_e32 v120, 0
	v_mov_b32_e32 v121, 0
	v_mov_b32_e32 v134, 0
	v_mov_b32_e32 v135, 0
	v_mov_b32_e32 v136, 0
	v_mov_b32_e32 v137, 0
	v_mov_b32_e32 v130, 0
	v_mov_b32_e32 v131, 0
	v_mov_b32_e32 v132, 0
	v_mov_b32_e32 v133, 0
	v_mov_b32_e32 v126, 0
	v_mov_b32_e32 v127, 0
	v_mov_b32_e32 v128, 0
	v_mov_b32_e32 v129, 0
	v_mov_b32_e32 v122, 0
	v_mov_b32_e32 v123, 0
	v_mov_b32_e32 v124, 0
	v_mov_b32_e32 v125, 0
	v_mov_b32_e32 v114, 0
	v_mov_b32_e32 v115, 0
	v_mov_b32_e32 v116, 0
	v_mov_b32_e32 v117, 0
	v_mov_b32_e32 v106, 0
	v_mov_b32_e32 v107, 0
	v_mov_b32_e32 v108, 0
	v_mov_b32_e32 v109, 0
	v_mov_b32_e32 v110, 0
	v_mov_b32_e32 v111, 0
	v_mov_b32_e32 v112, 0
	v_mov_b32_e32 v113, 0
	v_mov_b32_e32 v102, 0
	v_mov_b32_e32 v103, 0
	v_mov_b32_e32 v104, 0
	v_mov_b32_e32 v105, 0
	s_cmp_lt_u32 s92, 4
	s_cbranch_scc1 .Lattn_older
	s_setprio 1
.Lattn_older:
	s_waitcnt lgkmcnt(8)
	v_mfma_f32_16x16x32_bf16 v[150:153], v[178:181], v[74:77], v[66:69]
	v_mfma_f32_16x16x32_bf16 v[154:157], v[186:189], v[74:77], v[66:69]
	v_mfma_f32_16x16x32_bf16 v[162:165], v[186:189], v[82:85], v[66:69]
	v_mfma_f32_16x16x32_bf16 v[150:153], v[182:185], v[70:73], v[150:153]
	v_mfma_f32_16x16x32_bf16 v[154:157], v[190:193], v[70:73], v[154:157]
	v_mfma_f32_16x16x32_bf16 v[162:165], v[190:193], v[78:81], v[162:165]
	s_waitcnt lgkmcnt(0)
	ds_read_b128 v[178:181], v194 offset:4608
	ds_read_b128 v[182:185], v194 offset:4672
	ds_read_b128 v[186:189], v194 offset:6912
	ds_read_b128 v[190:193], v194 offset:6976
	ds_read_b64_tr_b16 v[216:217], v195 offset:4608
	ds_read_b64_tr_b16 v[218:219], v195 offset:6912
	ds_read_b64_tr_b16 v[220:221], v195 offset:4640
	ds_read_b64_tr_b16 v[222:223], v195 offset:6944
	ds_read_b64_tr_b16 v[224:225], v195 offset:4672
	ds_read_b64_tr_b16 v[226:227], v195 offset:6976
	ds_read_b64_tr_b16 v[228:229], v195 offset:4704
	ds_read_b64_tr_b16 v[230:231], v195 offset:7008

.Lattn_end4:
	s_setprio 0
	s_ashr_i32 s19, s18, 31
	s_lshl_b64 s[6:7], s[18:19], 14
	s_add_u32 s18, s6, s20
	s_addc_u32 s19, s7, s21
	s_lshl_b64 s[6:7], s[18:19], 5
	s_add_u32 s6, s24, s6
	s_addc_u32 s7, s25, s7
	s_lshl_b32 s9, s16, 2
	s_add_u32 s6, s6, s9
	s_addc_u32 s7, s7, 0
	s_lshl_b64 s[10:11], s[18:19], 10
	s_add_u32 s10, s22, s10
	s_addc_u32 s11, s23, s11
	s_lshl_b32 s9, s16, 7
	s_add_u32 s10, s10, s9
	s_addc_u32 s11, s11, 0
	v_mul_u32_u24_e32 v1, s14, v17
	v_lshlrev_b32_e32 v2, 10, v1
	v_lshl_add_u32 v2, v148, 5, v2
	v_lshlrev_b32_e32 v3, 5, v1
	v_cvt_pk_bf16_f32 v150, v134, v135
	v_cvt_pk_bf16_f32 v151, v136, v137
	v_cvt_pk_bf16_f32 v152, v130, v131
	v_cvt_pk_bf16_f32 v153, v132, v133
	v_cvt_pk_bf16_f32 v154, v126, v127
	v_cvt_pk_bf16_f32 v155, v128, v129
	v_cvt_pk_bf16_f32 v156, v122, v123
	v_cvt_pk_bf16_f32 v157, v124, v125
	v_cvt_pk_bf16_f32 v158, v114, v115
	v_cvt_pk_bf16_f32 v159, v116, v117
	v_cvt_pk_bf16_f32 v160, v106, v107
	v_cvt_pk_bf16_f32 v161, v108, v109
	v_cvt_pk_bf16_f32 v162, v110, v111
	v_cvt_pk_bf16_f32 v163, v112, v113
	v_cvt_pk_bf16_f32 v164, v102, v103
	v_cvt_pk_bf16_f32 v165, v104, v105
	s_nop 1
	v_permlane32_swap_b32_e32 v150, v154
	v_permlane32_swap_b32_e32 v152, v156
	v_permlane32_swap_b32_e32 v151, v155
	v_permlane32_swap_b32_e32 v153, v157
	v_permlane32_swap_b32_e32 v158, v162
	v_permlane32_swap_b32_e32 v160, v164
	v_permlane32_swap_b32_e32 v159, v163
	v_permlane32_swap_b32_e32 v161, v165
	s_nop 1
	v_permlane16_swap_b32_e32 v150, v152
	v_permlane16_swap_b32_e32 v154, v156
	v_permlane16_swap_b32_e32 v151, v153
	v_permlane16_swap_b32_e32 v155, v157
	v_permlane16_swap_b32_e32 v158, v160
	v_permlane16_swap_b32_e32 v162, v164
	v_permlane16_swap_b32_e32 v159, v161
	v_permlane16_swap_b32_e32 v163, v165
	global_store_dwordx4 v2, v[150:153], s[10:11]
	global_store_dwordx4 v2, v[154:157], s[10:11] offset:16
	s_lshl_b32 s9, s14, 14
	s_add_u32 s10, s10, s9
	s_addc_u32 s11, s11, 0
	global_store_dwordx4 v2, v[158:161], s[10:11]
	global_store_dwordx4 v2, v[162:165], s[10:11] offset:16
	v_cmp_eq_u32_e32 vcc, 0, v148
	s_and_saveexec_b64 s[34:35], vcc
	global_store_dword v3, v138, s[6:7]
	s_lshl_b32 s9, s14, 9
	s_add_u32 s6, s6, s9
	s_addc_u32 s7, s7, 0
	global_store_dword v3, v118, s[6:7]
	s_or_b64 exec, exec, s[34:35]
	s_branch .LBB0_331
